# A/B of lever 4: static s_setprio 1 on the leading wave group (wr==0) instead of the trailing group for each GEMM phase
# baseline (speedup 1.0000x reference)
; #define PG8_STAGE(bufoff, gbase, voff) do { _Pragma("unroll") for (int _i = 0; _i < 2; ++_i) \
;         __builtin_amdgcn_global_load_lds((const __attribute__((address_space(1))) unsigned*)((const char*)(gbase) + (voff)[_i]), (LAS unsigned*)(lds + (bufoff) + ldsw + _i * 8192), 16, 0, 0); } while (0)
; #define PG8_BAR __builtin_amdgcn_s_barrier()
; template <class Epi, class SchedT, bool ALIGN_EPI, bool SP2>
; __device__ __forceinline__ void gemm_phase(LAS unsigned char* lds, const int ldk, const int nt, const SchedT& S, const Epi& E) {
;     ...
;     const int wid = __builtin_amdgcn_readfirstlane(tid >> 6), lane = tid & 63, wr = wid >> 2, wc = wid & 3, fr = lane & 15, fq = lane >> 4;
;     const int K = ldk;
;     unsigned voffA[2], voffB[2];
; #pragma unroll
;     for (int i = 0; i < 2; ++i) { int R, C; stage_rc(tid * 16 + i * 8192, R, C); const int Rb = 2 * (R & ~31) + perm32(R & 31);
;         voffA[i] = (unsigned)(R * K + C) * 2u; voffB[i] = (unsigned)(Rb * K + C) * 2u; }
;     const size_t kstep = (size_t)(BK * 2);
;     const size_t hstep = (size_t)HALF * K * 2;
;     const size_t hstepB = (size_t)32 * K * 2;
;     const unsigned ldsw = (unsigned)wid * 1024u;
;     const int aoff = lds_byte(wr * 64 + fr, fq * 8), boff = lds_byte(wc * 32 + fr, fq * 8);
;     ...
;     Unit cur, nxt; int ui = 0;
;     if (!S.next(0, cur)) return;
;     f32x4 acc[2][2][4][2];
; #pragma unroll
;     for (int a = 0; a < 2; ++a)
; #pragma unroll
;         for (int b = 0; b < 2; ++b)
; #pragma unroll
;             for (int m = 0; m < 4; ++m)
; #pragma unroll
;                 for (int n = 0; n < 2; ++n) acc[a][b][m][n] = (f32x4){0.f, 0.f, 0.f, 0.f};
;     bf16x8 At[4][2], B0[2][2], B1[2][2];
;     const char* cA; const char* cB; S.ptrs(cur, cA, cB);
;     if constexpr (SP2) {
;         PG8_STAGE(PG8_SB(0, 0), cB, voffB); PG8_STAGE(PG8_SB(0, 1), cB + hstepB, voffB); PG8_STAGE(PG8_SA(0, 0), cA, voffA); PG8_STAGE(PG8_SA(0, 1), cA + hstep, voffA);
;         if (wr == 1) PG8_BAR;
.LBB0_112:
	s_mul_i32 s12, s16, 0x7500000
	v_writelane_b32 v163, s12, 36
	s_lshl_b32 s12, s16, 19
	s_mov_b32 s13, s23
	v_writelane_b32 v163, s12, 37
	s_mov_b32 s17, s23
	s_and_b64 vcc, exec, s[0:1]
	v_writelane_b32 v163, s13, 38
	v_writelane_b32 v163, s16, 39
	s_lshl_b64 s[0:1], s[16:17], 17
	s_nop 0
	v_writelane_b32 v163, s17, 40
	v_writelane_b32 v163, s0, 41
	s_nop 1
	v_writelane_b32 v163, s1, 42
	s_cbranch_vccnz .LBB0_358
	v_ashrrev_i32_e32 v3, 31, v0
	v_lshrrev_b32_e32 v3, 26, v3
	v_add_u32_e32 v3, v0, v3
	v_ashrrev_i32_e32 v10, 6, v3
	v_bfe_i32 v3, v0, 27, 1
	v_lshlrev_b32_e32 v2, 4, v0
	v_lshrrev_b32_e32 v3, 22, v3
	v_add_u32_e32 v3, v2, v3
	v_and_b32_e32 v3, 0xfffffc00, v3
	v_sub_u32_e32 v3, v2, v3
	v_lshrrev_b32_e32 v4, 4, v3
	v_bitop3_b32 v3, v4, v3, 32 bitop3:0x6c
	v_ashrrev_i32_e32 v5, 31, v3
	v_lshrrev_b32_e32 v5, 26, v5
	v_add_u32_e32 v5, v3, v5
	v_lshlrev_b32_e32 v4, 3, v10
	v_ashrrev_i32_e32 v11, 6, v5
	v_and_b32_e32 v5, 0xc0, v5
	v_and_b32_e32 v4, -16, v4
	v_sub_u32_e32 v3, v3, v5
	v_add_u32_e32 v4, v11, v4
	v_ashrrev_i16_sdwa v3, v244, sext(v3) dst_sel:DWORD dst_unused:UNUSED_PAD src0_sel:DWORD src1_sel:BYTE_0
	v_readlane_b32 s0, v163, 39
	v_lshlrev_b32_e32 v6, 5, v10
	v_bfe_i32 v12, v3, 0, 16
	v_lshlrev_b32_e32 v3, 1, v4
	v_lshrrev_b32_e32 v5, 2, v4
	s_mul_i32 s0, s0, 0x7500000
	v_and_b32_e32 v6, 32, v6
	v_and_b32_e32 v5, 4, v5
	v_and_b32_e32 v7, 3, v11
	v_and_b32_e32 v3, 0xfffd8, v3
	v_readlane_b32 s1, v163, 40
	s_add_u32 s0, s44, s0
	v_or3_b32 v3, v7, v5, v3
	v_add_lshl_u32 v5, v6, v12, 1
	v_add_u32_e32 v2, 0x2000, v2
	s_addc_u32 s1, s45, 0
	v_lshl_add_u32 v158, v3, 12, v5
	v_ashrrev_i32_e32 v3, 31, v2
	s_add_u32 s22, s0, 0x200000
	v_lshrrev_b32_e32 v3, 22, v3
	s_addc_u32 s84, s1, 0
	v_add_u32_e32 v3, v2, v3
	s_add_u32 s85, s44, 0xec00000
	v_ashrrev_i32_e32 v13, 10, v3
	s_addc_u32 s86, s45, 0
	s_ashr_i32 s0, s18, 6
	v_mul_i32_i24_e32 v3, 0x400, v13
	v_sub_u32_e32 v2, v2, v3
	s_ashr_i32 s94, s18, 8
	s_lshl_b32 s87, s0, 10
	v_lshrrev_b32_e32 v3, 4, v2
	s_cmp_eq_u32 s20, 0
	v_bitop3_b32 v2, v3, v2, 32 bitop3:0x6c
	s_cselect_b32 s12, s82, s51
	v_lshl_add_u32 v156, v4, 12, v5
	v_ashrrev_i32_e32 v4, 31, v2
	s_cselect_b32 s1, s86, s84
	s_cselect_b32 s17, s85, s22
	s_cselect_b32 s16, s51, s82
	s_cselect_b32 s19, s84, s86
	s_cselect_b32 s21, s22, s85
	s_ashr_i32 s13, s12, 31
	v_lshrrev_b32_e32 v4, 26, v4
	s_lshl_b64 s[12:13], s[12:13], 20
	v_add_u32_e32 v4, v2, v4
	s_add_u32 s12, s17, s12
	v_lshlrev_b32_e32 v3, 3, v13
	v_ashrrev_i32_e32 v14, 6, v4
	v_and_b32_e32 v4, 0xc0, v4
	s_addc_u32 s13, s1, s13
	s_ashr_i32 s17, s16, 31
	v_and_b32_e32 v3, -16, v3
	v_sub_u32_e32 v2, v2, v4
	s_lshl_b64 s[16:17], s[16:17], 20
	v_add_u32_e32 v3, v14, v3
	v_ashrrev_i16_sdwa v2, v244, sext(v2) dst_sel:DWORD dst_unused:UNUSED_PAD src0_sel:DWORD src1_sel:BYTE_0
	s_add_u32 s16, s21, s16
	v_lshlrev_b32_e32 v5, 5, v13
	v_bfe_i32 v15, v2, 0, 16
	v_lshlrev_b32_e32 v2, 1, v3
	v_lshrrev_b32_e32 v4, 2, v3
	s_addc_u32 s17, s19, s17
	s_add_i32 s88, s87, 0
	v_and_b32_e32 v5, 32, v5
	v_and_b32_e32 v4, 4, v4
	v_and_b32_e32 v6, 3, v14
	v_and_b32_e32 v2, 0xfffd8, v2
	s_add_i32 m0, s88, 0x10000
	v_or3_b32 v2, v6, v4, v2
	v_add_lshl_u32 v4, v5, v15, 1
	global_load_lds_dwordx4 v158, s[16:17]
	s_add_i32 m0, s88, 0x12000
	v_lshl_add_u32 v174, v2, 12, v4
	s_add_u32 s30, s16, 0x20000
	global_load_lds_dwordx4 v174, s[16:17]
	s_addc_u32 s31, s17, 0
	s_add_i32 m0, s88, 0x14000
	s_add_i32 s89, s88, 0x2000
	global_load_lds_dwordx4 v158, s[30:31]
	s_add_i32 m0, s88, 0x16000
	v_lshl_add_u32 v160, v3, 12, v4
	global_load_lds_dwordx4 v174, s[30:31]
	s_mov_b32 m0, s88
	s_add_u32 s30, s12, 0x80000
	global_load_lds_dwordx4 v156, s[12:13]
	s_mov_b32 m0, s89
	s_addc_u32 s31, s13, 0
	s_add_i32 s90, s88, 0x4000
	global_load_lds_dwordx4 v160, s[12:13]
	s_mov_b32 m0, s90
	s_add_i32 s91, s88, 0x6000
	global_load_lds_dwordx4 v156, s[30:31]
	s_mov_b32 m0, s91
	v_mov_b32_e32 v159, v1
	global_load_lds_dwordx4 v160, s[30:31]
	v_mov_b32_e32 v175, v1
	v_mov_b32_e32 v157, v1
	v_mov_b32_e32 v161, v1
	s_cmp_eq_u32 s94, 1
	v_lshl_add_u64 v[8:9], s[16:17], 0, v[158:159]
	v_lshl_add_u64 v[6:7], s[16:17], 0, v[174:175]
	v_lshl_add_u64 v[2:3], s[12:13], 0, v[156:157]
	s_cselect_b64 s[46:47], -1, 0
	s_cmp_lg_u32 s94, 1
	v_lshl_add_u64 v[4:5], s[12:13], 0, v[160:161]
	s_setprio 1
	s_cbranch_scc1 .LBB0_115
	s_barrier
	s_setprio 0

; #define PG8_STAGE(bufoff, gbase, voff) do { _Pragma("unroll") for (int _i = 0; _i < 2; ++_i) \
;         __builtin_amdgcn_global_load_lds((const __attribute__((address_space(1))) unsigned*)((const char*)(gbase) + (voff)[_i]), (LAS unsigned*)(lds + (bufoff) + ldsw + _i * 8192), 16, 0, 0); } while (0)
; #define PG8_BAR __builtin_amdgcn_s_barrier()
; template <class Epi, class SchedT, bool ALIGN_EPI, bool SP2>
; __device__ __forceinline__ void gemm_phase(LAS unsigned char* lds, const int ldk, const int nt, const SchedT& S, const Epi& E) {
;     ...
;     const int wid = __builtin_amdgcn_readfirstlane(tid >> 6), lane = tid & 63, wr = wid >> 2, wc = wid & 3, fr = lane & 15, fq = lane >> 4;
;     const int K = ldk;
;     unsigned voffA[2], voffB[2];
; #pragma unroll
;     for (int i = 0; i < 2; ++i) { int R, C; stage_rc(tid * 16 + i * 8192, R, C); const int Rb = 2 * (R & ~31) + perm32(R & 31);
;         voffA[i] = (unsigned)(R * K + C) * 2u; voffB[i] = (unsigned)(Rb * K + C) * 2u; }
;     const size_t kstep = (size_t)(BK * 2);
;     const size_t hstep = (size_t)HALF * K * 2;
;     const size_t hstepB = (size_t)32 * K * 2;
;     const unsigned ldsw = (unsigned)wid * 1024u;
;     const int aoff = lds_byte(wr * 64 + fr, fq * 8), boff = lds_byte(wc * 32 + fr, fq * 8);
;     ...
;     Unit cur, nxt; int ui = 0;
;     if (!S.next(0, cur)) return;
;     f32x4 acc[2][2][4][2];
; #pragma unroll
;     for (int a = 0; a < 2; ++a)
; #pragma unroll
;         for (int b = 0; b < 2; ++b)
; #pragma unroll
;             for (int m = 0; m < 4; ++m)
; #pragma unroll
;                 for (int n = 0; n < 2; ++n) acc[a][b][m][n] = (f32x4){0.f, 0.f, 0.f, 0.f};
;     bf16x8 At[4][2], B0[2][2], B1[2][2];
;     const char* cA; const char* cB; S.ptrs(cur, cA, cB);
;     if constexpr (SP2) {
;         PG8_STAGE(PG8_SB(0, 0), cB, voffB); PG8_STAGE(PG8_SB(0, 1), cB + hstepB, voffB); PG8_STAGE(PG8_SA(0, 0), cA, voffA); PG8_STAGE(PG8_SA(0, 1), cA + hstep, voffA);
;         if (wr == 1) PG8_BAR;
.LBB0_523:
	v_readlane_b32 s18, v163, 43
	v_readlane_b32 s19, v163, 44
	s_and_b64 vcc, exec, s[18:19]
	s_cbranch_vccnz .LBB0_607
	v_ashrrev_i32_e32 v3, 31, v0
	v_lshrrev_b32_e32 v3, 26, v3
	v_add_u32_e32 v3, v0, v3
	v_ashrrev_i32_e32 v10, 6, v3
	v_bfe_i32 v3, v0, 27, 1
	v_lshlrev_b32_e32 v2, 4, v0
	v_lshrrev_b32_e32 v3, 22, v3
	v_add_u32_e32 v3, v2, v3
	v_and_b32_e32 v3, 0xfffffc00, v3
	v_sub_u32_e32 v3, v2, v3
	v_lshrrev_b32_e32 v4, 4, v3
	v_bitop3_b32 v3, v4, v3, 32 bitop3:0x6c
	v_ashrrev_i32_e32 v5, 31, v3
	v_lshrrev_b32_e32 v5, 26, v5
	v_add_u32_e32 v5, v3, v5
	v_lshlrev_b32_e32 v4, 3, v10
	v_ashrrev_i32_e32 v11, 6, v5
	v_and_b32_e32 v5, 0xc0, v5
	v_and_b32_e32 v4, -16, v4
	v_sub_u32_e32 v3, v3, v5
	v_add_u32_e32 v4, v11, v4
	v_ashrrev_i16_sdwa v3, v244, sext(v3) dst_sel:DWORD dst_unused:UNUSED_PAD src0_sel:DWORD src1_sel:BYTE_0
	v_lshlrev_b32_e32 v6, 5, v10
	v_bfe_i32 v12, v3, 0, 16
	v_lshlrev_b32_e32 v3, 1, v4
	v_lshrrev_b32_e32 v5, 2, v4
	v_and_b32_e32 v6, 32, v6
	v_and_b32_e32 v5, 4, v5
	v_and_b32_e32 v7, 3, v11
	v_and_b32_e32 v3, 0xfffd8, v3
	v_or3_b32 v3, v7, v5, v3
	v_add_lshl_u32 v5, v6, v12, 1
	v_add_u32_e32 v2, 0x2000, v2
	v_lshl_add_u32 v134, v3, 12, v5
	v_ashrrev_i32_e32 v3, 31, v2
	v_lshrrev_b32_e32 v3, 22, v3
	v_add_u32_e32 v3, v2, v3
	v_ashrrev_i32_e32 v13, 10, v3
	v_readlane_b32 s18, v163, 39
	v_mul_i32_i24_e32 v3, 0x400, v13
	s_mul_i32 s13, s18, 0x7500000
	v_sub_u32_e32 v2, v2, v3
	s_add_u32 s13, s0, s13
	v_lshrrev_b32_e32 v3, 4, v2
	s_addc_u32 s17, s1, 0
	v_bitop3_b32 v2, v3, v2, 32 bitop3:0x6c
	s_add_u32 s21, s0, 0x1fc00000
	v_lshl_add_u32 v132, v4, 12, v5
	v_ashrrev_i32_e32 v4, 31, v2
	s_addc_u32 s22, s1, 0
	v_lshrrev_b32_e32 v4, 26, v4
	s_add_u32 s54, s13, 0x2600000
	v_add_u32_e32 v4, v2, v4
	v_readlane_b32 s19, v163, 40
	s_addc_u32 s55, s17, 0
	s_ashr_i32 s38, s20, 6
	v_lshlrev_b32_e32 v3, 3, v13
	v_ashrrev_i32_e32 v14, 6, v4
	v_and_b32_e32 v4, 0xc0, v4
	s_ashr_i32 s17, s16, 31
	s_ashr_i32 s13, s12, 31
	v_and_b32_e32 v3, -16, v3
	v_sub_u32_e32 v2, v2, v4
	s_ashr_i32 s39, s20, 8
	s_lshl_b32 s56, s38, 10
	s_lshl_b64 s[18:19], s[16:17], 20
	s_lshl_b64 s[30:31], s[12:13], 20
	v_add_u32_e32 v3, v14, v3
	v_ashrrev_i16_sdwa v2, v244, sext(v2) dst_sel:DWORD dst_unused:UNUSED_PAD src0_sel:DWORD src1_sel:BYTE_0
	s_add_u32 s36, s54, s30
	v_lshlrev_b32_e32 v5, 5, v13
	v_bfe_i32 v15, v2, 0, 16
	v_lshlrev_b32_e32 v2, 1, v3
	v_lshrrev_b32_e32 v4, 2, v3
	s_addc_u32 s37, s55, s31
	s_add_i32 s57, s56, 0
	v_and_b32_e32 v5, 32, v5
	v_and_b32_e32 v4, 4, v4
	v_and_b32_e32 v6, 3, v14
	v_and_b32_e32 v2, 0xfffd8, v2
	s_add_i32 m0, s57, 0x10000
	v_or3_b32 v2, v6, v4, v2
	v_add_lshl_u32 v4, v5, v15, 1
	global_load_lds_dwordx4 v134, s[36:37]
	s_add_i32 m0, s57, 0x12000
	v_lshl_add_u32 v138, v2, 12, v4
	s_add_u32 s30, s36, 0x20000
	global_load_lds_dwordx4 v138, s[36:37]
	s_addc_u32 s31, s37, 0
	s_add_i32 m0, s57, 0x14000
	v_lshl_add_u32 v136, v3, 12, v4
	global_load_lds_dwordx4 v134, s[30:31]
	s_add_i32 m0, s57, 0x16000
	s_add_u32 s34, s21, s18
	s_addc_u32 s35, s22, s19
	s_add_i32 s58, s57, 0x2000
	global_load_lds_dwordx4 v138, s[30:31]
	s_mov_b32 m0, s57
	s_add_u32 s18, s34, 0x80000
	global_load_lds_dwordx4 v132, s[34:35]
	s_mov_b32 m0, s58
	s_addc_u32 s19, s35, 0
	s_add_i32 s59, s57, 0x4000
	global_load_lds_dwordx4 v136, s[34:35]
	s_mov_b32 m0, s59
	s_add_i32 s60, s57, 0x6000
	global_load_lds_dwordx4 v132, s[18:19]
	s_mov_b32 m0, s60
	v_mov_b32_e32 v135, v1
	global_load_lds_dwordx4 v136, s[18:19]
	v_mov_b32_e32 v139, v1
	v_mov_b32_e32 v133, v1
	v_mov_b32_e32 v137, v1
	s_cmp_eq_u32 s39, 1
	v_lshl_add_u64 v[8:9], s[36:37], 0, v[134:135]
	v_lshl_add_u64 v[6:7], s[36:37], 0, v[138:139]
	v_lshl_add_u64 v[2:3], s[34:35], 0, v[132:133]
	s_cselect_b64 s[18:19], -1, 0
	s_cmp_lg_u32 s39, 1
	v_lshl_add_u64 v[4:5], s[34:35], 0, v[136:137]
	s_setprio 1
	s_cbranch_scc1 .LBB0_526
	s_barrier
	s_setprio 0

; #define PG8_STAGE(bufoff, gbase, voff) do { _Pragma("unroll") for (int _i = 0; _i < 2; ++_i) \
;         __builtin_amdgcn_global_load_lds((const __attribute__((address_space(1))) unsigned*)((const char*)(gbase) + (voff)[_i]), (LAS unsigned*)(lds + (bufoff) + ldsw + _i * 8192), 16, 0, 0); } while (0)
; #define PG8_BAR __builtin_amdgcn_s_barrier()
; template <class Epi, class SchedT, bool ALIGN_EPI, bool SP2>
; __device__ __forceinline__ void gemm_phase(LAS unsigned char* lds, const int ldk, const int nt, const SchedT& S, const Epi& E) {
;     ...
;     const int wid = __builtin_amdgcn_readfirstlane(tid >> 6), lane = tid & 63, wr = wid >> 2, wc = wid & 3, fr = lane & 15, fq = lane >> 4;
;     const int K = ldk;
;     unsigned voffA[2], voffB[2];
; #pragma unroll
;     for (int i = 0; i < 2; ++i) { int R, C; stage_rc(tid * 16 + i * 8192, R, C); const int Rb = 2 * (R & ~31) + perm32(R & 31);
;         voffA[i] = (unsigned)(R * K + C) * 2u; voffB[i] = (unsigned)(Rb * K + C) * 2u; }
;     const size_t kstep = (size_t)(BK * 2);
;     const size_t hstep = (size_t)HALF * K * 2;
;     const size_t hstepB = (size_t)32 * K * 2;
;     const unsigned ldsw = (unsigned)wid * 1024u;
;     const int aoff = lds_byte(wr * 64 + fr, fq * 8), boff = lds_byte(wc * 32 + fr, fq * 8);
;     ...
;     Unit cur, nxt; int ui = 0;
;     if (!S.next(0, cur)) return;
;     f32x4 acc[2][2][4][2];
; #pragma unroll
;     for (int a = 0; a < 2; ++a)
; #pragma unroll
;         for (int b = 0; b < 2; ++b)
; #pragma unroll
;             for (int m = 0; m < 4; ++m)
; #pragma unroll
;                 for (int n = 0; n < 2; ++n) acc[a][b][m][n] = (f32x4){0.f, 0.f, 0.f, 0.f};
;     bf16x8 At[4][2], B0[2][2], B1[2][2];
;     const char* cA; const char* cB; S.ptrs(cur, cA, cB);
;     if constexpr (SP2) {
;         PG8_STAGE(PG8_SB(0, 0), cB, voffB); PG8_STAGE(PG8_SB(0, 1), cB + hstepB, voffB); PG8_STAGE(PG8_SA(0, 0), cA, voffA); PG8_STAGE(PG8_SA(0, 1), cA + hstep, voffA);
;         if (wr == 1) PG8_BAR;
.LBB0_657:
	v_readlane_b32 s18, v163, 37
	v_readlane_b32 s19, v163, 38
	s_or_b32 s30, s18, 0x40000
	v_readlane_b32 s18, v163, 43
	v_readlane_b32 s19, v163, 44
	s_and_b64 vcc, exec, s[18:19]
	s_mov_b32 s31, s23
	s_cbranch_vccnz .LBB0_691
	v_ashrrev_i32_e32 v0, 31, v16
	v_lshrrev_b32_e32 v0, 26, v0
	v_add_u32_e32 v0, v16, v0
	v_ashrrev_i32_e32 v10, 6, v0
	v_bfe_i32 v0, v16, 27, 1
	v_lshlrev_b32_e32 v2, 4, v16
	v_lshrrev_b32_e32 v0, 22, v0
	v_add_u32_e32 v0, v2, v0
	v_and_b32_e32 v0, 0xfffffc00, v0
	v_sub_u32_e32 v0, v2, v0
	v_lshrrev_b32_e32 v3, 4, v0
	v_bitop3_b32 v0, v3, v0, 32 bitop3:0x6c
	v_ashrrev_i32_e32 v4, 31, v0
	v_lshrrev_b32_e32 v4, 26, v4
	v_add_u32_e32 v4, v0, v4
	v_lshlrev_b32_e32 v3, 3, v10
	v_ashrrev_i32_e32 v11, 6, v4
	v_and_b32_e32 v4, 0xc0, v4
	v_and_b32_e32 v3, -16, v3
	v_sub_u32_e32 v0, v0, v4
	v_add_u32_e32 v3, v11, v3
	v_ashrrev_i16_sdwa v0, v244, sext(v0) dst_sel:DWORD dst_unused:UNUSED_PAD src0_sel:DWORD src1_sel:BYTE_0
	v_lshlrev_b32_e32 v5, 5, v10
	v_bfe_i32 v12, v0, 0, 16
	v_lshlrev_b32_e32 v0, 1, v3
	v_lshrrev_b32_e32 v4, 2, v3
	v_and_b32_e32 v5, 32, v5
	v_and_b32_e32 v4, 4, v4
	v_and_b32_e32 v6, 3, v11
	v_and_b32_e32 v0, 0xfffd8, v0
	v_or3_b32 v0, v6, v4, v0
	v_add_lshl_u32 v4, v5, v12, 1
	v_add_u32_e32 v2, 0x2000, v2
	v_lshl_add_u32 v130, v3, 12, v4
	v_ashrrev_i32_e32 v3, 31, v2
	v_lshrrev_b32_e32 v3, 22, v3
	v_add_u32_e32 v3, v2, v3
	v_ashrrev_i32_e32 v13, 10, v3
	v_readlane_b32 s18, v163, 39
	v_mul_i32_i24_e32 v3, 0x400, v13
	s_mul_i32 s13, s18, 0x7500000
	v_sub_u32_e32 v2, v2, v3
	s_add_u32 s13, s0, s13
	v_lshrrev_b32_e32 v3, 4, v2
	s_addc_u32 s17, s1, 0
	v_bitop3_b32 v2, v3, v2, 32 bitop3:0x6c
	s_add_u32 s21, s0, 0x25c00000
	v_lshl_add_u32 v0, v0, 12, v4
	v_ashrrev_i32_e32 v4, 31, v2
	s_addc_u32 s58, s1, 0
	v_lshrrev_b32_e32 v4, 26, v4
	s_add_u32 s59, s13, 0x2e00000
	v_add_u32_e32 v4, v2, v4
	v_readlane_b32 s19, v163, 40
	s_addc_u32 s60, s17, 0
	s_ashr_i32 s22, s20, 6
	v_lshlrev_b32_e32 v3, 3, v13
	v_ashrrev_i32_e32 v14, 6, v4
	v_and_b32_e32 v4, 0xc0, v4
	s_ashr_i32 s17, s16, 31
	s_ashr_i32 s13, s12, 31
	v_and_b32_e32 v3, -16, v3
	v_sub_u32_e32 v2, v2, v4
	s_ashr_i32 s38, s20, 8
	s_lshl_b32 s61, s22, 10
	s_lshl_b64 s[18:19], s[16:17], 20
	s_lshl_b64 s[34:35], s[12:13], 20
	v_add_u32_e32 v3, v14, v3
	v_ashrrev_i16_sdwa v2, v244, sext(v2) dst_sel:DWORD dst_unused:UNUSED_PAD src0_sel:DWORD src1_sel:BYTE_0
	s_add_u32 s36, s59, s34
	v_lshlrev_b32_e32 v5, 5, v13
	v_bfe_i32 v15, v2, 0, 16
	v_lshlrev_b32_e32 v2, 1, v3
	v_lshrrev_b32_e32 v4, 2, v3
	s_addc_u32 s37, s60, s35
	s_add_i32 s17, s61, 0
	v_and_b32_e32 v5, 32, v5
	v_and_b32_e32 v4, 4, v4
	v_and_b32_e32 v6, 3, v14
	v_and_b32_e32 v2, 0xfffd8, v2
	s_add_i32 m0, s17, 0x10000
	v_or3_b32 v2, v6, v4, v2
	v_add_lshl_u32 v4, v5, v15, 1
	global_load_lds_dwordx4 v0, s[36:37]
	s_add_i32 m0, s17, 0x12000
	v_lshl_add_u32 v134, v2, 12, v4
	s_add_u32 s34, s36, 0x20000
	global_load_lds_dwordx4 v134, s[36:37]
	s_addc_u32 s35, s37, 0
	s_add_i32 m0, s17, 0x14000
	v_lshl_add_u32 v132, v3, 12, v4
	global_load_lds_dwordx4 v0, s[34:35]
	s_add_i32 m0, s17, 0x16000
	v_mov_b32_e32 v135, v1
	global_load_lds_dwordx4 v134, s[34:35]
	s_add_u32 s34, s21, s18
	s_addc_u32 s35, s58, s19
	s_add_i32 s62, s17, 0x2000
	s_mov_b32 m0, s17
	s_add_u32 s18, s34, 0x80000
	global_load_lds_dwordx4 v130, s[34:35]
	s_mov_b32 m0, s62
	s_addc_u32 s19, s35, 0
	s_add_i32 s63, s17, 0x4000
	global_load_lds_dwordx4 v132, s[34:35]
	s_mov_b32 m0, s63
	s_add_i32 s81, s17, 0x6000
	global_load_lds_dwordx4 v130, s[18:19]
	s_mov_b32 m0, s81
	v_mov_b32_e32 v131, v1
	global_load_lds_dwordx4 v132, s[18:19]
	v_mov_b32_e32 v133, v1
	s_cmp_eq_u32 s38, 1
	v_lshl_add_u64 v[8:9], s[36:37], 0, v[0:1]
	v_lshl_add_u64 v[6:7], s[36:37], 0, v[134:135]
	v_lshl_add_u64 v[2:3], s[34:35], 0, v[130:131]
	s_cselect_b64 s[18:19], -1, 0
	s_cmp_lg_u32 s38, 1
	v_lshl_add_u64 v[4:5], s[34:35], 0, v[132:133]
	s_setprio 1
	s_cbranch_scc1 .LBB0_660
	s_barrier
	s_setprio 0

; #define PG8_STAGE(bufoff, gbase, voff) do { _Pragma("unroll") for (int _i = 0; _i < 2; ++_i) \
;         __builtin_amdgcn_global_load_lds((const __attribute__((address_space(1))) unsigned*)((const char*)(gbase) + (voff)[_i]), (LAS unsigned*)(lds + (bufoff) + ldsw + _i * 8192), 16, 0, 0); } while (0)
; #define PG8_BAR __builtin_amdgcn_s_barrier()
; template <class Epi, class SchedT, bool ALIGN_EPI, bool SP2>
; __device__ __forceinline__ void gemm_phase(LAS unsigned char* lds, const int ldk, const int nt, const SchedT& S, const Epi& E) {
;     ...
;     const int wid = __builtin_amdgcn_readfirstlane(tid >> 6), lane = tid & 63, wr = wid >> 2, wc = wid & 3, fr = lane & 15, fq = lane >> 4;
;     const int K = ldk;
;     unsigned voffA[2], voffB[2];
; #pragma unroll
;     for (int i = 0; i < 2; ++i) { int R, C; stage_rc(tid * 16 + i * 8192, R, C); const int Rb = 2 * (R & ~31) + perm32(R & 31);
;         voffA[i] = (unsigned)(R * K + C) * 2u; voffB[i] = (unsigned)(Rb * K + C) * 2u; }
;     const size_t kstep = (size_t)(BK * 2);
;     const size_t hstep = (size_t)HALF * K * 2;
;     const size_t hstepB = (size_t)32 * K * 2;
;     const unsigned ldsw = (unsigned)wid * 1024u;
;     const int aoff = lds_byte(wr * 64 + fr, fq * 8), boff = lds_byte(wc * 32 + fr, fq * 8);
;     ...
;     Unit cur, nxt; int ui = 0;
;     if (!S.next(0, cur)) return;
;     f32x4 acc[2][2][4][2];
; #pragma unroll
;     for (int a = 0; a < 2; ++a)
; #pragma unroll
;         for (int b = 0; b < 2; ++b)
; #pragma unroll
;             for (int m = 0; m < 4; ++m)
; #pragma unroll
;                 for (int n = 0; n < 2; ++n) acc[a][b][m][n] = (f32x4){0.f, 0.f, 0.f, 0.f};
;     bf16x8 At[4][2], B0[2][2], B1[2][2];
;     const char* cA; const char* cB; S.ptrs(cur, cA, cB);
;     if constexpr (SP2) {
;         PG8_STAGE(PG8_SB(0, 0), cB, voffB); PG8_STAGE(PG8_SB(0, 1), cB + hstepB, voffB); PG8_STAGE(PG8_SA(0, 0), cA, voffA); PG8_STAGE(PG8_SA(0, 1), cA + hstep, voffA);
;         if (wr == 1) PG8_BAR;
.LBB0_741:
	v_readlane_b32 s18, v163, 39
	v_readlane_b32 s44, v254, 1
	s_mul_i32 s13, s18, 0x20400
	v_readlane_b32 s52, v254, 9
	v_readlane_b32 s19, v163, 40
	s_mov_b32 s20, s18
	v_readlane_b32 s53, v254, 10
	s_add_u32 s18, s52, s13
	v_readlane_b32 s54, v254, 11
	s_addc_u32 s19, s53, 0
	s_mul_i32 s13, s20, 0xac00
	v_readlane_b32 s55, v254, 12
	s_add_u32 s20, s54, s13
	s_addc_u32 s21, s55, 0
	s_and_b64 vcc, exec, s[0:1]
	v_readlane_b32 s45, v254, 2
	v_readlane_b32 s46, v254, 3
	v_readlane_b32 s47, v254, 4
	v_readlane_b32 s48, v254, 5
	v_readlane_b32 s49, v254, 6
	v_readlane_b32 s50, v254, 7
	v_readlane_b32 s51, v254, 8
	v_readlane_b32 s56, v254, 13
	v_readlane_b32 s57, v254, 14
	v_readlane_b32 s58, v254, 15
	v_readlane_b32 s59, v254, 16
	s_cbranch_vccnz .LBB0_791
	v_ashrrev_i32_e32 v0, 31, v16
	v_lshrrev_b32_e32 v0, 26, v0
	v_add_u32_e32 v0, v16, v0
	v_ashrrev_i32_e32 v10, 6, v0
	v_bfe_i32 v0, v16, 27, 1
	v_lshlrev_b32_e32 v2, 4, v16
	v_lshrrev_b32_e32 v0, 22, v0
	v_add_u32_e32 v0, v2, v0
	v_and_b32_e32 v0, 0xfffffc00, v0
	v_sub_u32_e32 v0, v2, v0
	v_lshrrev_b32_e32 v3, 4, v0
	v_bitop3_b32 v0, v3, v0, 32 bitop3:0x6c
	v_ashrrev_i32_e32 v4, 31, v0
	v_lshrrev_b32_e32 v4, 26, v4
	v_add_u32_e32 v4, v0, v4
	v_lshlrev_b32_e32 v3, 3, v10
	v_ashrrev_i32_e32 v11, 6, v4
	v_and_b32_e32 v4, 0xc0, v4
	v_and_b32_e32 v3, -16, v3
	v_sub_u32_e32 v0, v0, v4
	v_add_u32_e32 v3, v11, v3
	v_ashrrev_i16_sdwa v0, v244, sext(v0) dst_sel:DWORD dst_unused:UNUSED_PAD src0_sel:DWORD src1_sel:BYTE_0
	v_lshlrev_b32_e32 v5, 5, v10
	v_bfe_i32 v12, v0, 0, 16
	v_lshlrev_b32_e32 v0, 1, v3
	v_lshrrev_b32_e32 v4, 2, v3
	v_and_b32_e32 v5, 32, v5
	v_and_b32_e32 v4, 4, v4
	v_and_b32_e32 v6, 3, v11
	v_and_b32_e32 v0, 0xfffd8, v0
	v_or3_b32 v0, v6, v4, v0
	v_add_lshl_u32 v4, v5, v12, 1
	v_add_u32_e32 v2, 0x2000, v2
	v_lshl_add_u32 v146, v3, 12, v4
	v_ashrrev_i32_e32 v3, 31, v2
	v_lshrrev_b32_e32 v3, 22, v3
	v_add_u32_e32 v3, v2, v3
	v_ashrrev_i32_e32 v13, 10, v3
	v_mul_i32_i24_e32 v3, 0x400, v13
	v_readlane_b32 s0, v163, 36
	v_sub_u32_e32 v2, v2, v3
	s_add_u32 s0, s38, s0
	v_lshrrev_b32_e32 v3, 4, v2
	s_addc_u32 s1, s39, 0
	v_bitop3_b32 v2, v3, v2, 32 bitop3:0x6c
	s_add_u32 s22, s38, 0x10c00000
	v_lshl_add_u32 v0, v0, 12, v4
	v_ashrrev_i32_e32 v4, 31, v2
	s_addc_u32 s81, s39, 0
	v_lshrrev_b32_e32 v4, 26, v4
	s_add_u32 s82, s0, 0x3600000
	v_add_u32_e32 v4, v2, v4
	s_addc_u32 s83, s1, 0
	v_lshlrev_b32_e32 v3, 3, v13
	v_ashrrev_i32_e32 v14, 6, v4
	v_and_b32_e32 v4, 0xc0, v4
	s_ashr_i32 s41, s40, 6
	s_ashr_i32 s13, s12, 31
	s_ashr_i32 s17, s16, 31
	s_ashr_i32 s50, s40, 8
	v_and_b32_e32 v3, -16, v3
	v_sub_u32_e32 v2, v2, v4
	s_lshl_b32 s84, s41, 10
	s_lshl_b64 s[0:1], s[12:13], 20
	s_lshl_b64 s[34:35], s[16:17], 20
	v_add_u32_e32 v3, v14, v3
	v_ashrrev_i16_sdwa v2, v244, sext(v2) dst_sel:DWORD dst_unused:UNUSED_PAD src0_sel:DWORD src1_sel:BYTE_0
	s_add_u32 s36, s82, s34
	v_lshlrev_b32_e32 v5, 5, v13
	v_bfe_i32 v15, v2, 0, 16
	v_lshlrev_b32_e32 v2, 1, v3
	v_lshrrev_b32_e32 v4, 2, v3
	s_addc_u32 s37, s83, s35
	s_add_i32 s85, s84, 0
	v_and_b32_e32 v5, 32, v5
	v_and_b32_e32 v4, 4, v4
	v_and_b32_e32 v6, 3, v14
	v_and_b32_e32 v2, 0xfffd8, v2
	s_add_i32 m0, s85, 0x10000
	v_or3_b32 v2, v6, v4, v2
	v_add_lshl_u32 v4, v5, v15, 1
	global_load_lds_dwordx4 v0, s[36:37]
	s_add_i32 m0, s85, 0x12000
	v_lshl_add_u32 v150, v2, 12, v4
	s_add_u32 s34, s36, 0x20000
	global_load_lds_dwordx4 v150, s[36:37]
	s_addc_u32 s35, s37, 0
	s_add_i32 m0, s85, 0x14000
	v_lshl_add_u32 v148, v3, 12, v4
	global_load_lds_dwordx4 v0, s[34:35]
	s_add_i32 m0, s85, 0x16000
	v_mov_b32_e32 v151, v1
	global_load_lds_dwordx4 v150, s[34:35]
	s_add_u32 s34, s22, s0
	s_addc_u32 s35, s81, s1
	s_add_i32 s86, s85, 0x2000
	s_mov_b32 m0, s85
	s_add_u32 s0, s34, 0x80000
	global_load_lds_dwordx4 v146, s[34:35]
	s_mov_b32 m0, s86
	s_addc_u32 s1, s35, 0
	s_add_i32 s87, s85, 0x4000
	global_load_lds_dwordx4 v148, s[34:35]
	s_mov_b32 m0, s87
	s_add_i32 s88, s85, 0x6000
	global_load_lds_dwordx4 v146, s[0:1]
	s_mov_b32 m0, s88
	v_mov_b32_e32 v147, v1
	global_load_lds_dwordx4 v148, s[0:1]
	v_mov_b32_e32 v149, v1
	s_cmp_eq_u32 s50, 1
	v_mov_b32_e32 v162, v242
	v_lshl_add_u64 v[8:9], s[36:37], 0, v[0:1]
	v_lshl_add_u64 v[6:7], s[36:37], 0, v[150:151]
	v_lshl_add_u64 v[2:3], s[34:35], 0, v[146:147]
	s_cselect_b64 s[52:53], -1, 0
	s_cmp_lg_u32 s50, 1
	v_lshl_add_u64 v[4:5], s[34:35], 0, v[148:149]
	s_setprio 1
	s_cbranch_scc1 .LBB0_744
	s_barrier
	s_setprio 0

; #define PG8_STAGE(bufoff, gbase, voff) do { _Pragma("unroll") for (int _i = 0; _i < 2; ++_i) \
;         __builtin_amdgcn_global_load_lds((const __attribute__((address_space(1))) unsigned*)((const char*)(gbase) + (voff)[_i]), (LAS unsigned*)(lds + (bufoff) + ldsw + _i * 8192), 16, 0, 0); } while (0)
; #define PG8_BAR __builtin_amdgcn_s_barrier()
; template <class Epi, class SchedT, bool ALIGN_EPI, bool SP2>
; __device__ __forceinline__ void gemm_phase(LAS unsigned char* lds, const int ldk, const int nt, const SchedT& S, const Epi& E) {
;     ...
;     const int wid = __builtin_amdgcn_readfirstlane(tid >> 6), lane = tid & 63, wr = wid >> 2, wc = wid & 3, fr = lane & 15, fq = lane >> 4;
;     const int K = ldk;
;     unsigned voffA[2], voffB[2];
; #pragma unroll
;     for (int i = 0; i < 2; ++i) { int R, C; stage_rc(tid * 16 + i * 8192, R, C); const int Rb = 2 * (R & ~31) + perm32(R & 31);
;         voffA[i] = (unsigned)(R * K + C) * 2u; voffB[i] = (unsigned)(Rb * K + C) * 2u; }
;     const size_t kstep = (size_t)(BK * 2);
;     const size_t hstep = (size_t)HALF * K * 2;
;     const size_t hstepB = (size_t)32 * K * 2;
;     const unsigned ldsw = (unsigned)wid * 1024u;
;     const int aoff = lds_byte(wr * 64 + fr, fq * 8), boff = lds_byte(wc * 32 + fr, fq * 8);
;     ...
;     Unit cur, nxt; int ui = 0;
;     if (!S.next(0, cur)) return;
;     f32x4 acc[2][2][4][2];
; #pragma unroll
;     for (int a = 0; a < 2; ++a)
; #pragma unroll
;         for (int b = 0; b < 2; ++b)
; #pragma unroll
;             for (int m = 0; m < 4; ++m)
; #pragma unroll
;                 for (int n = 0; n < 2; ++n) acc[a][b][m][n] = (f32x4){0.f, 0.f, 0.f, 0.f};
;     bf16x8 At[4][2], B0[2][2], B1[2][2];
;     const char* cA; const char* cB; S.ptrs(cur, cA, cB);
;     if constexpr (SP2) {
;         PG8_STAGE(PG8_SB(0, 0), cB, voffB); PG8_STAGE(PG8_SB(0, 1), cB + hstepB, voffB); PG8_STAGE(PG8_SA(0, 0), cA, voffA); PG8_STAGE(PG8_SA(0, 1), cA + hstep, voffA);
;         if (wr == 1) PG8_BAR;
.LBB0_937:
	v_readlane_b32 s12, v163, 43
	v_readlane_b32 s13, v163, 44
	s_and_b64 vcc, exec, s[12:13]
	s_cbranch_vccnz .LBB0_971
	v_ashrrev_i32_e32 v0, 31, v18
	v_lshrrev_b32_e32 v0, 26, v0
	v_add_u32_e32 v0, v18, v0
	v_ashrrev_i32_e32 v10, 6, v0
	v_bfe_i32 v0, v18, 27, 1
	v_lshlrev_b32_e32 v2, 4, v18
	v_lshrrev_b32_e32 v0, 22, v0
	v_add_u32_e32 v0, v2, v0
	v_and_b32_e32 v0, 0xfffffc00, v0
	v_sub_u32_e32 v0, v2, v0
	v_lshrrev_b32_e32 v3, 4, v0
	v_bitop3_b32 v0, v3, v0, 32 bitop3:0x6c
	v_ashrrev_i32_e32 v4, 31, v0
	v_readlane_b32 s12, v163, 36
	v_lshrrev_b32_e32 v4, 26, v4
	s_add_u32 s12, s0, s12
	v_lshlrev_b32_e32 v3, 3, v10
	v_add_u32_e32 v4, v0, v4
	s_addc_u32 s13, s1, 0
	v_and_b32_e32 v3, -16, v3
	v_ashrrev_i32_e32 v12, 6, v4
	v_and_b32_e32 v4, 0xc0, v4
	s_add_u32 s48, s0, 0x21800000
	v_add_u32_e32 v3, v12, v3
	v_lshlrev_b32_e32 v5, 5, v10
	v_sub_u32_e32 v0, v0, v4
	s_addc_u32 s49, s1, 0
	v_and_b32_e32 v11, 32, v5
	v_ashrrev_i16_sdwa v0, v244, sext(v0) dst_sel:DWORD dst_unused:UNUSED_PAD src0_sel:DWORD src1_sel:BYTE_0
	v_lshlrev_b32_e32 v4, 1, v3
	v_lshrrev_b32_e32 v5, 2, v3
	s_add_u32 s50, s12, 0x6100000
	v_bfe_i32 v13, v0, 0, 16
	v_and_b32_e32 v5, 4, v5
	v_and_b32_e32 v6, 3, v12
	v_and_b32_e32 v4, 0x1ffffd8, v4
	s_movk_i32 s12, 0x1580
	v_add_u32_e32 v0, v11, v13
	v_or3_b32 v4, v6, v5, v4
	v_mul_lo_u32 v3, v3, s12
	v_add_lshl_u32 v130, v0, v3, 1
	v_mul_lo_u32 v3, v4, s12
	v_add_u32_e32 v2, 0x2000, v2
	v_add_lshl_u32 v0, v3, v0, 1
	v_ashrrev_i32_e32 v3, 31, v2
	v_lshrrev_b32_e32 v3, 22, v3
	v_add_u32_e32 v3, v2, v3
	v_ashrrev_i32_e32 v14, 10, v3
	v_mul_i32_i24_e32 v3, 0x400, v14
	v_sub_u32_e32 v2, v2, v3
	v_lshrrev_b32_e32 v3, 4, v2
	v_bitop3_b32 v2, v3, v2, 32 bitop3:0x6c
	v_ashrrev_i32_e32 v4, 31, v2
	v_lshrrev_b32_e32 v4, 26, v4
	v_lshlrev_b32_e32 v3, 3, v14
	v_add_u32_e32 v4, v2, v4
	v_and_b32_e32 v3, -16, v3
	v_ashrrev_i32_e32 v16, 6, v4
	v_and_b32_e32 v4, 0xc0, v4
	v_add_u32_e32 v3, v16, v3
	v_lshlrev_b32_e32 v5, 5, v14
	v_sub_u32_e32 v2, v2, v4
	v_and_b32_e32 v15, 32, v5
	v_ashrrev_i16_sdwa v2, v244, sext(v2) dst_sel:DWORD dst_unused:UNUSED_PAD src0_sel:DWORD src1_sel:BYTE_0
	v_lshlrev_b32_e32 v4, 1, v3
	v_lshrrev_b32_e32 v5, 2, v3
	s_addc_u32 s51, s13, 0
	s_ashr_i32 s37, s36, 6
	v_bfe_i32 v17, v2, 0, 16
	v_and_b32_e32 v5, 4, v5
	v_and_b32_e32 v6, 3, v16
	v_and_b32_e32 v4, 0x1ffffd8, v4
	v_add_u32_e32 v2, v15, v17
	v_or3_b32 v4, v6, v5, v4
	v_mul_lo_u32 v3, v3, s12
	s_ashr_i32 s38, s36, 8
	s_lshl_b32 s52, s37, 10
	s_mul_i32 s13, s22, 0x2b0000
	v_add_lshl_u32 v132, v2, v3, 1
	v_mul_lo_u32 v3, v4, s12
	s_mul_hi_i32 s12, s22, 0x2b0000
	s_add_u32 s16, s50, s13
	s_addc_u32 s17, s51, s12
	s_add_i32 s53, s52, 0
	s_add_i32 m0, s53, 0x10000
	v_add_lshl_u32 v134, v3, v2, 1
	global_load_lds_dwordx4 v0, s[16:17]
	s_add_i32 m0, s53, 0x12000
	s_add_u32 s12, s16, 0x56000
	global_load_lds_dwordx4 v134, s[16:17]
	s_addc_u32 s13, s17, 0
	s_add_i32 m0, s53, 0x14000
	s_mul_i32 s19, s63, 0x2b0000
	global_load_lds_dwordx4 v0, s[12:13]
	s_add_i32 m0, s53, 0x16000
	s_mul_hi_i32 s18, s63, 0x2b0000
	global_load_lds_dwordx4 v134, s[12:13]
	s_add_u32 s12, s48, s19
	s_addc_u32 s13, s49, s18
	s_add_i32 s54, s53, 0x2000
	s_mov_b32 m0, s53
	s_add_u32 s18, s12, 0x158000
	global_load_lds_dwordx4 v130, s[12:13]
	s_mov_b32 m0, s54
	s_addc_u32 s19, s13, 0
	s_add_i32 s55, s53, 0x4000
	global_load_lds_dwordx4 v132, s[12:13]
	s_mov_b32 m0, s55
	s_add_i32 s56, s53, 0x6000
	global_load_lds_dwordx4 v130, s[18:19]
	s_mov_b32 m0, s56
	v_mov_b32_e32 v135, v1
	global_load_lds_dwordx4 v132, s[18:19]
	v_mov_b32_e32 v131, v1
	v_mov_b32_e32 v133, v1
	s_cmp_eq_u32 s38, 1
	v_lshl_add_u64 v[8:9], s[16:17], 0, v[0:1]
	v_lshl_add_u64 v[6:7], s[16:17], 0, v[134:135]
	v_lshl_add_u64 v[2:3], s[12:13], 0, v[130:131]
	s_cselect_b64 s[18:19], -1, 0
	s_cmp_lg_u32 s38, 1
	v_lshl_add_u64 v[4:5], s[12:13], 0, v[132:133]
	s_setprio 1
	s_cbranch_scc1 .LBB0_940
	s_barrier
	s_setprio 0
